# hand-written B2 prompt scan: scanner waves publish y partials (4B/lane) instead of full state; DPP waits filled
# speedup vs baseline: 1.0719x; 1.0719x over previous
.LBB0_287:
	v_readlane_b32 s0, v214, 29
	v_readlane_b32 s1, v214, 30
	s_andn2_b64 vcc, exec, s[0:1]
	s_mov_b64 s[54:55], s[34:35]
	s_cbranch_vccnz .LBB0_316
	v_readlane_b32 s22, v216, 0
.Lb2_u_loop:
	s_waitcnt vmcnt(0) lgkmcnt(0)
	s_barrier
	s_and_b32 s20, s22, 7
	s_lshl_b32 s20, s20, 3
	s_lshr_b32 s21, s22, 5
	s_add_i32 s20, s20, s21
	s_bfe_u32 s33, s22, 0x20003
	s_mul_i32 s28, s20, 0x300000
	s_add_u32 s28, s28, 0xcf90000
	s_add_u32 s28, s94, s28
	s_addc_u32 s29, s95, 0
	v_readfirstlane_b32 s21, v133
	s_cmpk_lt_u32 s21, 0x100
	s_cbranch_scc0 .Lb2_loader
	v_lshrrev_b32_e32 v10, 4, v133
	v_and_b32_e32 v11, 15, v133
	v_lshlrev_b32_e32 v6, 4, v11
	s_lshl_b32 s21, s33, 4
	s_addk_i32 s21, 0x140
	v_add_u32_e32 v7, s21, v10
	v_lshlrev_b32_e32 v7, 2, v7
	v_lshlrev_b32_e32 v8, 6, v10
	v_lshl_add_u32 v8, v11, 2, v8
	v_add_u32_e32 v8, 0xc000, v8
	v_lshlrev_b32_e32 v9, 8, v10
	v_lshl_add_u32 v9, v11, 4, v9
	s_lshl_b32 s21, s76, 6
	s_add_i32 s21, s21, s20
	s_lshl_b32 s21, s21, 14
	s_lshl_b32 s23, s33, 12
	s_add_i32 s21, s21, s23
	s_add_u32 s21, s21, 0x412c000
	s_add_u32 s40, s92, s21
	s_addc_u32 s41, s93, 0
	v_mov_b32_e32 v0, 0
	v_mov_b32_e32 v1, 0
	v_mov_b32_e32 v2, 0
	v_mov_b32_e32 v3, 0
	s_movk_i32 s34, 0x40
	s_setprio 2
	s_barrier
	ds_read_b128 v[12:15], v6 offset:0
	ds_read_b128 v[16:19], v6 offset:256
	ds_read_b128 v[20:23], v6 offset:512
	ds_read_b128 v[24:27], v6 offset:768
	ds_read_b128 v[28:31], v6 offset:1024
	ds_read_b32 v32, v7 offset:0
	ds_read_b128 v[36:39], v6 offset:1536
	ds_read_b128 v[40:43], v6 offset:1792
	ds_read_b128 v[44:47], v6 offset:2048
	ds_read_b128 v[48:51], v6 offset:2304
	ds_read_b128 v[52:55], v6 offset:2560
	ds_read_b32 v56, v7 offset:1536
	ds_read_b128 v[68:71], v6 offset:3072
	ds_read_b128 v[72:75], v6 offset:3328
	ds_read_b128 v[76:79], v6 offset:3584
	ds_read_b128 v[80:83], v6 offset:3840
	ds_read_b128 v[84:87], v6 offset:4096
	ds_read_b32 v88, v7 offset:3072
	s_waitcnt lgkmcnt(0)
.Lb2_scan_loop:
	s_waitcnt lgkmcnt(14)
	v_mul_f32_e32 v4, v0, v16
	v_mul_f32_e32 v5, v0, v28
	v_fmac_f32_e32 v4, v1, v17
	v_fmac_f32_e32 v5, v1, v29
	v_fmac_f32_e32 v4, v2, v18
	v_fmac_f32_e32 v5, v2, v30
	v_fmac_f32_e32 v4, v3, v19
	v_fmac_f32_e32 v5, v3, v31
	v_mul_f32_e32 v0, v0, v12
	v_add_f32_dpp v4, v4, v4 quad_perm:[1,0,3,2] row_mask:0xf bank_mask:0xf bound_ctrl:1
	v_mul_f32_e32 v1, v1, v13
	ds_write_b32 v8, v5 offset:0
	v_add_f32_dpp v4, v4, v4 quad_perm:[2,3,0,1] row_mask:0xf bank_mask:0xf bound_ctrl:1
	v_mul_f32_e32 v2, v2, v14
	v_mul_f32_e32 v3, v3, v15
	v_add_f32_dpp v4, v4, v4 row_half_mirror row_mask:0xf bank_mask:0xf bound_ctrl:1
	v_fmac_f32_e32 v0, v32, v24
	v_fmac_f32_e32 v1, v32, v25
	v_add_f32_dpp v4, v4, v4 row_mirror row_mask:0xf bank_mask:0xf bound_ctrl:1
	v_fmac_f32_e32 v2, v32, v26
	v_fmac_f32_e32 v3, v32, v27
	v_fma_f32 v0, -v4, v20, v0
	v_fma_f32 v1, -v4, v21, v1
	v_fma_f32 v2, -v4, v22, v2
	v_fma_f32 v3, -v4, v23, v3
	ds_read_b128 v[92:95], v6 offset:4608
	ds_read_b128 v[96:99], v6 offset:4864
	ds_read_b128 v[100:103], v6 offset:5120
	ds_read_b128 v[104:107], v6 offset:5376
	ds_read_b128 v[108:111], v6 offset:5632
	ds_read_b32 v112, v7 offset:4608
	s_waitcnt lgkmcnt(14)
	v_mul_f32_e32 v4, v0, v40
	v_mul_f32_e32 v5, v0, v52
	v_fmac_f32_e32 v4, v1, v41
	v_fmac_f32_e32 v5, v1, v53
	v_fmac_f32_e32 v4, v2, v42
	v_fmac_f32_e32 v5, v2, v54
	v_fmac_f32_e32 v4, v3, v43
	v_fmac_f32_e32 v5, v3, v55
	v_mul_f32_e32 v0, v0, v36
	v_add_f32_dpp v4, v4, v4 quad_perm:[1,0,3,2] row_mask:0xf bank_mask:0xf bound_ctrl:1
	v_mul_f32_e32 v1, v1, v37
	ds_write_b32 v8, v5 offset:1024
	v_add_f32_dpp v4, v4, v4 quad_perm:[2,3,0,1] row_mask:0xf bank_mask:0xf bound_ctrl:1
	v_mul_f32_e32 v2, v2, v38
	v_mul_f32_e32 v3, v3, v39
	v_add_f32_dpp v4, v4, v4 row_half_mirror row_mask:0xf bank_mask:0xf bound_ctrl:1
	v_fmac_f32_e32 v0, v56, v48
	v_fmac_f32_e32 v1, v56, v49
	v_add_f32_dpp v4, v4, v4 row_mirror row_mask:0xf bank_mask:0xf bound_ctrl:1
	v_fmac_f32_e32 v2, v56, v50
	v_fmac_f32_e32 v3, v56, v51
	v_fma_f32 v0, -v4, v44, v0
	v_fma_f32 v1, -v4, v45, v1
	v_fma_f32 v2, -v4, v46, v2
	v_fma_f32 v3, -v4, v47, v3
	ds_read_b128 v[12:15], v6 offset:6144
	ds_read_b128 v[16:19], v6 offset:6400
	ds_read_b128 v[20:23], v6 offset:6656
	ds_read_b128 v[24:27], v6 offset:6912
	ds_read_b128 v[28:31], v6 offset:7168
	ds_read_b32 v32, v7 offset:6144
	s_waitcnt lgkmcnt(14)
	v_mul_f32_e32 v4, v0, v72
	v_mul_f32_e32 v5, v0, v84
	v_fmac_f32_e32 v4, v1, v73
	v_fmac_f32_e32 v5, v1, v85
	v_fmac_f32_e32 v4, v2, v74
	v_fmac_f32_e32 v5, v2, v86
	v_fmac_f32_e32 v4, v3, v75
	v_fmac_f32_e32 v5, v3, v87
	v_mul_f32_e32 v0, v0, v68
	v_add_f32_dpp v4, v4, v4 quad_perm:[1,0,3,2] row_mask:0xf bank_mask:0xf bound_ctrl:1
	v_mul_f32_e32 v1, v1, v69
	ds_write_b32 v8, v5 offset:2048
	v_add_f32_dpp v4, v4, v4 quad_perm:[2,3,0,1] row_mask:0xf bank_mask:0xf bound_ctrl:1
	v_mul_f32_e32 v2, v2, v70
	v_mul_f32_e32 v3, v3, v71
	v_add_f32_dpp v4, v4, v4 row_half_mirror row_mask:0xf bank_mask:0xf bound_ctrl:1
	v_fmac_f32_e32 v0, v88, v80
	v_fmac_f32_e32 v1, v88, v81
	v_add_f32_dpp v4, v4, v4 row_mirror row_mask:0xf bank_mask:0xf bound_ctrl:1
	v_fmac_f32_e32 v2, v88, v82
	v_fmac_f32_e32 v3, v88, v83
	v_fma_f32 v0, -v4, v76, v0
	v_fma_f32 v1, -v4, v77, v1
	v_fma_f32 v2, -v4, v78, v2
	v_fma_f32 v3, -v4, v79, v3
	ds_read_b128 v[36:39], v6 offset:7680
	ds_read_b128 v[40:43], v6 offset:7936
	ds_read_b128 v[44:47], v6 offset:8192
	ds_read_b128 v[48:51], v6 offset:8448
	ds_read_b128 v[52:55], v6 offset:8704
	ds_read_b32 v56, v7 offset:7680
	s_waitcnt lgkmcnt(14)
	v_mul_f32_e32 v4, v0, v96
	v_mul_f32_e32 v5, v0, v108
	v_fmac_f32_e32 v4, v1, v97
	v_fmac_f32_e32 v5, v1, v109
	v_fmac_f32_e32 v4, v2, v98
	v_fmac_f32_e32 v5, v2, v110
	v_fmac_f32_e32 v4, v3, v99
	v_fmac_f32_e32 v5, v3, v111
	v_mul_f32_e32 v0, v0, v92
	v_add_f32_dpp v4, v4, v4 quad_perm:[1,0,3,2] row_mask:0xf bank_mask:0xf bound_ctrl:1
	v_mul_f32_e32 v1, v1, v93
	ds_write_b32 v8, v5 offset:3072
	v_add_f32_dpp v4, v4, v4 quad_perm:[2,3,0,1] row_mask:0xf bank_mask:0xf bound_ctrl:1
	v_mul_f32_e32 v2, v2, v94
	v_mul_f32_e32 v3, v3, v95
	v_add_f32_dpp v4, v4, v4 row_half_mirror row_mask:0xf bank_mask:0xf bound_ctrl:1
	v_fmac_f32_e32 v0, v112, v104
	v_fmac_f32_e32 v1, v112, v105
	v_add_f32_dpp v4, v4, v4 row_mirror row_mask:0xf bank_mask:0xf bound_ctrl:1
	v_fmac_f32_e32 v2, v112, v106
	v_fmac_f32_e32 v3, v112, v107
	v_fma_f32 v0, -v4, v100, v0
	v_fma_f32 v1, -v4, v101, v1
	v_fma_f32 v2, -v4, v102, v2
	v_fma_f32 v3, -v4, v103, v3
	ds_read_b128 v[68:71], v6 offset:9216
	ds_read_b128 v[72:75], v6 offset:9472
	ds_read_b128 v[76:79], v6 offset:9728
	ds_read_b128 v[80:83], v6 offset:9984
	ds_read_b128 v[84:87], v6 offset:10240
	ds_read_b32 v88, v7 offset:9216
	s_waitcnt lgkmcnt(14)
	v_mul_f32_e32 v4, v0, v16
	v_mul_f32_e32 v5, v0, v28
	v_fmac_f32_e32 v4, v1, v17
	v_fmac_f32_e32 v5, v1, v29
	v_fmac_f32_e32 v4, v2, v18
	v_fmac_f32_e32 v5, v2, v30
	v_fmac_f32_e32 v4, v3, v19
	v_fmac_f32_e32 v5, v3, v31
	v_mul_f32_e32 v0, v0, v12
	v_add_f32_dpp v4, v4, v4 quad_perm:[1,0,3,2] row_mask:0xf bank_mask:0xf bound_ctrl:1
	v_mul_f32_e32 v1, v1, v13
	ds_write_b32 v8, v5 offset:4096
	v_add_f32_dpp v4, v4, v4 quad_perm:[2,3,0,1] row_mask:0xf bank_mask:0xf bound_ctrl:1
	v_mul_f32_e32 v2, v2, v14
	v_mul_f32_e32 v3, v3, v15
	v_add_f32_dpp v4, v4, v4 row_half_mirror row_mask:0xf bank_mask:0xf bound_ctrl:1
	v_fmac_f32_e32 v0, v32, v24
	v_fmac_f32_e32 v1, v32, v25
	v_add_f32_dpp v4, v4, v4 row_mirror row_mask:0xf bank_mask:0xf bound_ctrl:1
	v_fmac_f32_e32 v2, v32, v26
	v_fmac_f32_e32 v3, v32, v27
	v_fma_f32 v0, -v4, v20, v0
	v_fma_f32 v1, -v4, v21, v1
	v_fma_f32 v2, -v4, v22, v2
	v_fma_f32 v3, -v4, v23, v3
	ds_read_b128 v[92:95], v6 offset:10752
	ds_read_b128 v[96:99], v6 offset:11008
	ds_read_b128 v[100:103], v6 offset:11264
	ds_read_b128 v[104:107], v6 offset:11520
	ds_read_b128 v[108:111], v6 offset:11776
	ds_read_b32 v112, v7 offset:10752
	s_waitcnt lgkmcnt(14)
	v_mul_f32_e32 v4, v0, v40
	v_mul_f32_e32 v5, v0, v52
	v_fmac_f32_e32 v4, v1, v41
	v_fmac_f32_e32 v5, v1, v53
	v_fmac_f32_e32 v4, v2, v42
	v_fmac_f32_e32 v5, v2, v54
	v_fmac_f32_e32 v4, v3, v43
	v_fmac_f32_e32 v5, v3, v55
	v_mul_f32_e32 v0, v0, v36
	v_add_f32_dpp v4, v4, v4 quad_perm:[1,0,3,2] row_mask:0xf bank_mask:0xf bound_ctrl:1
	v_mul_f32_e32 v1, v1, v37
	ds_write_b32 v8, v5 offset:5120
	v_add_f32_dpp v4, v4, v4 quad_perm:[2,3,0,1] row_mask:0xf bank_mask:0xf bound_ctrl:1
	v_mul_f32_e32 v2, v2, v38
	v_mul_f32_e32 v3, v3, v39
	v_add_f32_dpp v4, v4, v4 row_half_mirror row_mask:0xf bank_mask:0xf bound_ctrl:1
	v_fmac_f32_e32 v0, v56, v48
	v_fmac_f32_e32 v1, v56, v49
	v_add_f32_dpp v4, v4, v4 row_mirror row_mask:0xf bank_mask:0xf bound_ctrl:1
	v_fmac_f32_e32 v2, v56, v50
	v_fmac_f32_e32 v3, v56, v51
	v_fma_f32 v0, -v4, v44, v0
	v_fma_f32 v1, -v4, v45, v1
	v_fma_f32 v2, -v4, v46, v2
	v_fma_f32 v3, -v4, v47, v3
	ds_read_b128 v[12:15], v6 offset:12288
	ds_read_b128 v[16:19], v6 offset:12544
	ds_read_b128 v[20:23], v6 offset:12800
	ds_read_b128 v[24:27], v6 offset:13056
	ds_read_b128 v[28:31], v6 offset:13312
	ds_read_b32 v32, v7 offset:12288
	s_waitcnt lgkmcnt(14)
	v_mul_f32_e32 v4, v0, v72
	v_mul_f32_e32 v5, v0, v84
	v_fmac_f32_e32 v4, v1, v73
	v_fmac_f32_e32 v5, v1, v85
	v_fmac_f32_e32 v4, v2, v74
	v_fmac_f32_e32 v5, v2, v86
	v_fmac_f32_e32 v4, v3, v75
	v_fmac_f32_e32 v5, v3, v87
	v_mul_f32_e32 v0, v0, v68
	v_add_f32_dpp v4, v4, v4 quad_perm:[1,0,3,2] row_mask:0xf bank_mask:0xf bound_ctrl:1
	v_mul_f32_e32 v1, v1, v69
	ds_write_b32 v8, v5 offset:6144
	v_add_f32_dpp v4, v4, v4 quad_perm:[2,3,0,1] row_mask:0xf bank_mask:0xf bound_ctrl:1
	v_mul_f32_e32 v2, v2, v70
	v_mul_f32_e32 v3, v3, v71
	v_add_f32_dpp v4, v4, v4 row_half_mirror row_mask:0xf bank_mask:0xf bound_ctrl:1
	v_fmac_f32_e32 v0, v88, v80
	v_fmac_f32_e32 v1, v88, v81
	v_add_f32_dpp v4, v4, v4 row_mirror row_mask:0xf bank_mask:0xf bound_ctrl:1
	v_fmac_f32_e32 v2, v88, v82
	v_fmac_f32_e32 v3, v88, v83
	v_fma_f32 v0, -v4, v76, v0
	v_fma_f32 v1, -v4, v77, v1
	v_fma_f32 v2, -v4, v78, v2
	v_fma_f32 v3, -v4, v79, v3
	ds_read_b128 v[36:39], v6 offset:13824
	ds_read_b128 v[40:43], v6 offset:14080
	ds_read_b128 v[44:47], v6 offset:14336
	ds_read_b128 v[48:51], v6 offset:14592
	ds_read_b128 v[52:55], v6 offset:14848
	ds_read_b32 v56, v7 offset:13824
	s_waitcnt lgkmcnt(14)
	v_mul_f32_e32 v4, v0, v96
	v_mul_f32_e32 v5, v0, v108
	v_fmac_f32_e32 v4, v1, v97
	v_fmac_f32_e32 v5, v1, v109
	v_fmac_f32_e32 v4, v2, v98
	v_fmac_f32_e32 v5, v2, v110
	v_fmac_f32_e32 v4, v3, v99
	v_fmac_f32_e32 v5, v3, v111
	v_mul_f32_e32 v0, v0, v92
	v_add_f32_dpp v4, v4, v4 quad_perm:[1,0,3,2] row_mask:0xf bank_mask:0xf bound_ctrl:1
	v_mul_f32_e32 v1, v1, v93
	ds_write_b32 v8, v5 offset:7168
	v_add_f32_dpp v4, v4, v4 quad_perm:[2,3,0,1] row_mask:0xf bank_mask:0xf bound_ctrl:1
	v_mul_f32_e32 v2, v2, v94
	v_mul_f32_e32 v3, v3, v95
	v_add_f32_dpp v4, v4, v4 row_half_mirror row_mask:0xf bank_mask:0xf bound_ctrl:1
	v_fmac_f32_e32 v0, v112, v104
	v_fmac_f32_e32 v1, v112, v105
	v_add_f32_dpp v4, v4, v4 row_mirror row_mask:0xf bank_mask:0xf bound_ctrl:1
	v_fmac_f32_e32 v2, v112, v106
	v_fmac_f32_e32 v3, v112, v107
	v_fma_f32 v0, -v4, v100, v0
	v_fma_f32 v1, -v4, v101, v1
	v_fma_f32 v2, -v4, v102, v2
	v_fma_f32 v3, -v4, v103, v3
	ds_read_b128 v[68:71], v6 offset:15360
	ds_read_b128 v[72:75], v6 offset:15616
	ds_read_b128 v[76:79], v6 offset:15872
	ds_read_b128 v[80:83], v6 offset:16128
	ds_read_b128 v[84:87], v6 offset:16384
	ds_read_b32 v88, v7 offset:15360
	s_waitcnt lgkmcnt(6)
	s_barrier
	s_waitcnt lgkmcnt(14)
	v_mul_f32_e32 v4, v0, v16
	v_mul_f32_e32 v5, v0, v28
	v_fmac_f32_e32 v4, v1, v17
	v_fmac_f32_e32 v5, v1, v29
	v_fmac_f32_e32 v4, v2, v18
	v_fmac_f32_e32 v5, v2, v30
	v_fmac_f32_e32 v4, v3, v19
	v_fmac_f32_e32 v5, v3, v31
	v_mul_f32_e32 v0, v0, v12
	v_add_f32_dpp v4, v4, v4 quad_perm:[1,0,3,2] row_mask:0xf bank_mask:0xf bound_ctrl:1
	v_mul_f32_e32 v1, v1, v13
	ds_write_b32 v8, v5 offset:8192
	v_add_f32_dpp v4, v4, v4 quad_perm:[2,3,0,1] row_mask:0xf bank_mask:0xf bound_ctrl:1
	v_mul_f32_e32 v2, v2, v14
	v_mul_f32_e32 v3, v3, v15
	v_add_f32_dpp v4, v4, v4 row_half_mirror row_mask:0xf bank_mask:0xf bound_ctrl:1
	v_fmac_f32_e32 v0, v32, v24
	v_fmac_f32_e32 v1, v32, v25
	v_add_f32_dpp v4, v4, v4 row_mirror row_mask:0xf bank_mask:0xf bound_ctrl:1
	v_fmac_f32_e32 v2, v32, v26
	v_fmac_f32_e32 v3, v32, v27
	v_fma_f32 v0, -v4, v20, v0
	v_fma_f32 v1, -v4, v21, v1
	v_fma_f32 v2, -v4, v22, v2
	v_fma_f32 v3, -v4, v23, v3
	ds_read_b128 v[92:95], v6 offset:16896
	ds_read_b128 v[96:99], v6 offset:17152
	ds_read_b128 v[100:103], v6 offset:17408
	ds_read_b128 v[104:107], v6 offset:17664
	ds_read_b128 v[108:111], v6 offset:17920
	ds_read_b32 v112, v7 offset:16896
	s_waitcnt lgkmcnt(14)
	v_mul_f32_e32 v4, v0, v40
	v_mul_f32_e32 v5, v0, v52
	v_fmac_f32_e32 v4, v1, v41
	v_fmac_f32_e32 v5, v1, v53
	v_fmac_f32_e32 v4, v2, v42
	v_fmac_f32_e32 v5, v2, v54
	v_fmac_f32_e32 v4, v3, v43
	v_fmac_f32_e32 v5, v3, v55
	v_mul_f32_e32 v0, v0, v36
	v_add_f32_dpp v4, v4, v4 quad_perm:[1,0,3,2] row_mask:0xf bank_mask:0xf bound_ctrl:1
	v_mul_f32_e32 v1, v1, v37
	ds_write_b32 v8, v5 offset:9216
	v_add_f32_dpp v4, v4, v4 quad_perm:[2,3,0,1] row_mask:0xf bank_mask:0xf bound_ctrl:1
	v_mul_f32_e32 v2, v2, v38
	v_mul_f32_e32 v3, v3, v39
	v_add_f32_dpp v4, v4, v4 row_half_mirror row_mask:0xf bank_mask:0xf bound_ctrl:1
	v_fmac_f32_e32 v0, v56, v48
	v_fmac_f32_e32 v1, v56, v49
	v_add_f32_dpp v4, v4, v4 row_mirror row_mask:0xf bank_mask:0xf bound_ctrl:1
	v_fmac_f32_e32 v2, v56, v50
	v_fmac_f32_e32 v3, v56, v51
	v_fma_f32 v0, -v4, v44, v0
	v_fma_f32 v1, -v4, v45, v1
	v_fma_f32 v2, -v4, v46, v2
	v_fma_f32 v3, -v4, v47, v3
	ds_read_b128 v[12:15], v6 offset:18432
	ds_read_b128 v[16:19], v6 offset:18688
	ds_read_b128 v[20:23], v6 offset:18944
	ds_read_b128 v[24:27], v6 offset:19200
	ds_read_b128 v[28:31], v6 offset:19456
	ds_read_b32 v32, v7 offset:18432
	s_waitcnt lgkmcnt(14)
	v_mul_f32_e32 v4, v0, v72
	v_mul_f32_e32 v5, v0, v84
	v_fmac_f32_e32 v4, v1, v73
	v_fmac_f32_e32 v5, v1, v85
	v_fmac_f32_e32 v4, v2, v74
	v_fmac_f32_e32 v5, v2, v86
	v_fmac_f32_e32 v4, v3, v75
	v_fmac_f32_e32 v5, v3, v87
	v_mul_f32_e32 v0, v0, v68
	v_add_f32_dpp v4, v4, v4 quad_perm:[1,0,3,2] row_mask:0xf bank_mask:0xf bound_ctrl:1
	v_mul_f32_e32 v1, v1, v69
	ds_write_b32 v8, v5 offset:10240
	v_add_f32_dpp v4, v4, v4 quad_perm:[2,3,0,1] row_mask:0xf bank_mask:0xf bound_ctrl:1
	v_mul_f32_e32 v2, v2, v70
	v_mul_f32_e32 v3, v3, v71
	v_add_f32_dpp v4, v4, v4 row_half_mirror row_mask:0xf bank_mask:0xf bound_ctrl:1
	v_fmac_f32_e32 v0, v88, v80
	v_fmac_f32_e32 v1, v88, v81
	v_add_f32_dpp v4, v4, v4 row_mirror row_mask:0xf bank_mask:0xf bound_ctrl:1
	v_fmac_f32_e32 v2, v88, v82
	v_fmac_f32_e32 v3, v88, v83
	v_fma_f32 v0, -v4, v76, v0
	v_fma_f32 v1, -v4, v77, v1
	v_fma_f32 v2, -v4, v78, v2
	v_fma_f32 v3, -v4, v79, v3
	ds_read_b128 v[36:39], v6 offset:19968
	ds_read_b128 v[40:43], v6 offset:20224
	ds_read_b128 v[44:47], v6 offset:20480
	ds_read_b128 v[48:51], v6 offset:20736
	ds_read_b128 v[52:55], v6 offset:20992
	ds_read_b32 v56, v7 offset:19968
	s_waitcnt lgkmcnt(14)
	v_mul_f32_e32 v4, v0, v96
	v_mul_f32_e32 v5, v0, v108
	v_fmac_f32_e32 v4, v1, v97
	v_fmac_f32_e32 v5, v1, v109
	v_fmac_f32_e32 v4, v2, v98
	v_fmac_f32_e32 v5, v2, v110
	v_fmac_f32_e32 v4, v3, v99
	v_fmac_f32_e32 v5, v3, v111
	v_mul_f32_e32 v0, v0, v92
	v_add_f32_dpp v4, v4, v4 quad_perm:[1,0,3,2] row_mask:0xf bank_mask:0xf bound_ctrl:1
	v_mul_f32_e32 v1, v1, v93
	ds_write_b32 v8, v5 offset:11264
	v_add_f32_dpp v4, v4, v4 quad_perm:[2,3,0,1] row_mask:0xf bank_mask:0xf bound_ctrl:1
	v_mul_f32_e32 v2, v2, v94
	v_mul_f32_e32 v3, v3, v95
	v_add_f32_dpp v4, v4, v4 row_half_mirror row_mask:0xf bank_mask:0xf bound_ctrl:1
	v_fmac_f32_e32 v0, v112, v104
	v_fmac_f32_e32 v1, v112, v105
	v_add_f32_dpp v4, v4, v4 row_mirror row_mask:0xf bank_mask:0xf bound_ctrl:1
	v_fmac_f32_e32 v2, v112, v106
	v_fmac_f32_e32 v3, v112, v107
	v_fma_f32 v0, -v4, v100, v0
	v_fma_f32 v1, -v4, v101, v1
	v_fma_f32 v2, -v4, v102, v2
	v_fma_f32 v3, -v4, v103, v3
	ds_read_b128 v[68:71], v6 offset:21504
	ds_read_b128 v[72:75], v6 offset:21760
	ds_read_b128 v[76:79], v6 offset:22016
	ds_read_b128 v[80:83], v6 offset:22272
	ds_read_b128 v[84:87], v6 offset:22528
	ds_read_b32 v88, v7 offset:21504
	s_waitcnt lgkmcnt(14)
	v_mul_f32_e32 v4, v0, v16
	v_mul_f32_e32 v5, v0, v28
	v_fmac_f32_e32 v4, v1, v17
	v_fmac_f32_e32 v5, v1, v29
	v_fmac_f32_e32 v4, v2, v18
	v_fmac_f32_e32 v5, v2, v30
	v_fmac_f32_e32 v4, v3, v19
	v_fmac_f32_e32 v5, v3, v31
	v_mul_f32_e32 v0, v0, v12
	v_add_f32_dpp v4, v4, v4 quad_perm:[1,0,3,2] row_mask:0xf bank_mask:0xf bound_ctrl:1
	v_mul_f32_e32 v1, v1, v13
	ds_write_b32 v8, v5 offset:12288
	v_add_f32_dpp v4, v4, v4 quad_perm:[2,3,0,1] row_mask:0xf bank_mask:0xf bound_ctrl:1
	v_mul_f32_e32 v2, v2, v14
	v_mul_f32_e32 v3, v3, v15
	v_add_f32_dpp v4, v4, v4 row_half_mirror row_mask:0xf bank_mask:0xf bound_ctrl:1
	v_fmac_f32_e32 v0, v32, v24
	v_fmac_f32_e32 v1, v32, v25
	v_add_f32_dpp v4, v4, v4 row_mirror row_mask:0xf bank_mask:0xf bound_ctrl:1
	v_fmac_f32_e32 v2, v32, v26
	v_fmac_f32_e32 v3, v32, v27
	v_fma_f32 v0, -v4, v20, v0
	v_fma_f32 v1, -v4, v21, v1
	v_fma_f32 v2, -v4, v22, v2
	v_fma_f32 v3, -v4, v23, v3
	ds_read_b128 v[92:95], v6 offset:23040
	ds_read_b128 v[96:99], v6 offset:23296
	ds_read_b128 v[100:103], v6 offset:23552
	ds_read_b128 v[104:107], v6 offset:23808
	ds_read_b128 v[108:111], v6 offset:24064
	ds_read_b32 v112, v7 offset:23040
	s_waitcnt lgkmcnt(14)
	v_mul_f32_e32 v4, v0, v40
	v_mul_f32_e32 v5, v0, v52
	v_fmac_f32_e32 v4, v1, v41
	v_fmac_f32_e32 v5, v1, v53
	v_fmac_f32_e32 v4, v2, v42
	v_fmac_f32_e32 v5, v2, v54
	v_fmac_f32_e32 v4, v3, v43
	v_fmac_f32_e32 v5, v3, v55
	v_mul_f32_e32 v0, v0, v36
	v_add_f32_dpp v4, v4, v4 quad_perm:[1,0,3,2] row_mask:0xf bank_mask:0xf bound_ctrl:1
	v_mul_f32_e32 v1, v1, v37
	ds_write_b32 v8, v5 offset:13312
	v_add_f32_dpp v4, v4, v4 quad_perm:[2,3,0,1] row_mask:0xf bank_mask:0xf bound_ctrl:1
	v_mul_f32_e32 v2, v2, v38
	v_mul_f32_e32 v3, v3, v39
	v_add_f32_dpp v4, v4, v4 row_half_mirror row_mask:0xf bank_mask:0xf bound_ctrl:1
	v_fmac_f32_e32 v0, v56, v48
	v_fmac_f32_e32 v1, v56, v49
	v_add_f32_dpp v4, v4, v4 row_mirror row_mask:0xf bank_mask:0xf bound_ctrl:1
	v_fmac_f32_e32 v2, v56, v50
	v_fmac_f32_e32 v3, v56, v51
	v_fma_f32 v0, -v4, v44, v0
	v_fma_f32 v1, -v4, v45, v1
	v_fma_f32 v2, -v4, v46, v2
	v_fma_f32 v3, -v4, v47, v3
	ds_read_b128 v[12:15], v6 offset:24576
	ds_read_b128 v[16:19], v6 offset:24832
	ds_read_b128 v[20:23], v6 offset:25088
	ds_read_b128 v[24:27], v6 offset:25344
	ds_read_b128 v[28:31], v6 offset:25600
	ds_read_b32 v32, v7 offset:24576
	s_waitcnt lgkmcnt(14)
	v_mul_f32_e32 v4, v0, v72
	v_mul_f32_e32 v5, v0, v84
	v_fmac_f32_e32 v4, v1, v73
	v_fmac_f32_e32 v5, v1, v85
	v_fmac_f32_e32 v4, v2, v74
	v_fmac_f32_e32 v5, v2, v86
	v_fmac_f32_e32 v4, v3, v75
	v_fmac_f32_e32 v5, v3, v87
	v_mul_f32_e32 v0, v0, v68
	v_add_f32_dpp v4, v4, v4 quad_perm:[1,0,3,2] row_mask:0xf bank_mask:0xf bound_ctrl:1
	v_mul_f32_e32 v1, v1, v69
	ds_write_b32 v8, v5 offset:14336
	v_add_f32_dpp v4, v4, v4 quad_perm:[2,3,0,1] row_mask:0xf bank_mask:0xf bound_ctrl:1
	v_mul_f32_e32 v2, v2, v70
	v_mul_f32_e32 v3, v3, v71
	v_add_f32_dpp v4, v4, v4 row_half_mirror row_mask:0xf bank_mask:0xf bound_ctrl:1
	v_fmac_f32_e32 v0, v88, v80
	v_fmac_f32_e32 v1, v88, v81
	v_add_f32_dpp v4, v4, v4 row_mirror row_mask:0xf bank_mask:0xf bound_ctrl:1
	v_fmac_f32_e32 v2, v88, v82
	v_fmac_f32_e32 v3, v88, v83
	v_fma_f32 v0, -v4, v76, v0
	v_fma_f32 v1, -v4, v77, v1
	v_fma_f32 v2, -v4, v78, v2
	v_fma_f32 v3, -v4, v79, v3
	ds_read_b128 v[36:39], v6 offset:26112
	ds_read_b128 v[40:43], v6 offset:26368
	ds_read_b128 v[44:47], v6 offset:26624
	ds_read_b128 v[48:51], v6 offset:26880
	ds_read_b128 v[52:55], v6 offset:27136
	ds_read_b32 v56, v7 offset:26112
	s_waitcnt lgkmcnt(14)
	v_mul_f32_e32 v4, v0, v96
	v_mul_f32_e32 v5, v0, v108
	v_fmac_f32_e32 v4, v1, v97
	v_fmac_f32_e32 v5, v1, v109
	v_fmac_f32_e32 v4, v2, v98
	v_fmac_f32_e32 v5, v2, v110
	v_fmac_f32_e32 v4, v3, v99
	v_fmac_f32_e32 v5, v3, v111
	v_mul_f32_e32 v0, v0, v92
	v_add_f32_dpp v4, v4, v4 quad_perm:[1,0,3,2] row_mask:0xf bank_mask:0xf bound_ctrl:1
	v_mul_f32_e32 v1, v1, v93
	ds_write_b32 v8, v5 offset:15360
	v_add_f32_dpp v4, v4, v4 quad_perm:[2,3,0,1] row_mask:0xf bank_mask:0xf bound_ctrl:1
	v_mul_f32_e32 v2, v2, v94
	v_mul_f32_e32 v3, v3, v95
	v_add_f32_dpp v4, v4, v4 row_half_mirror row_mask:0xf bank_mask:0xf bound_ctrl:1
	v_fmac_f32_e32 v0, v112, v104
	v_fmac_f32_e32 v1, v112, v105
	v_add_f32_dpp v4, v4, v4 row_mirror row_mask:0xf bank_mask:0xf bound_ctrl:1
	v_fmac_f32_e32 v2, v112, v106
	v_fmac_f32_e32 v3, v112, v107
	v_fma_f32 v0, -v4, v100, v0
	v_fma_f32 v1, -v4, v101, v1
	v_fma_f32 v2, -v4, v102, v2
	v_fma_f32 v3, -v4, v103, v3
	ds_read_b128 v[68:71], v6 offset:27648
	ds_read_b128 v[72:75], v6 offset:27904
	ds_read_b128 v[76:79], v6 offset:28160
	ds_read_b128 v[80:83], v6 offset:28416
	ds_read_b128 v[84:87], v6 offset:28672
	ds_read_b32 v88, v7 offset:27648
	s_waitcnt lgkmcnt(6)
	s_barrier
	s_waitcnt lgkmcnt(14)
	v_mul_f32_e32 v4, v0, v16
	v_mul_f32_e32 v5, v0, v28
	v_fmac_f32_e32 v4, v1, v17
	v_fmac_f32_e32 v5, v1, v29
	v_fmac_f32_e32 v4, v2, v18
	v_fmac_f32_e32 v5, v2, v30
	v_fmac_f32_e32 v4, v3, v19
	v_fmac_f32_e32 v5, v3, v31
	v_mul_f32_e32 v0, v0, v12
	v_add_f32_dpp v4, v4, v4 quad_perm:[1,0,3,2] row_mask:0xf bank_mask:0xf bound_ctrl:1
	v_mul_f32_e32 v1, v1, v13
	ds_write_b32 v8, v5 offset:0
	v_add_f32_dpp v4, v4, v4 quad_perm:[2,3,0,1] row_mask:0xf bank_mask:0xf bound_ctrl:1
	v_mul_f32_e32 v2, v2, v14
	v_mul_f32_e32 v3, v3, v15
	v_add_f32_dpp v4, v4, v4 row_half_mirror row_mask:0xf bank_mask:0xf bound_ctrl:1
	v_fmac_f32_e32 v0, v32, v24
	v_fmac_f32_e32 v1, v32, v25
	v_add_f32_dpp v4, v4, v4 row_mirror row_mask:0xf bank_mask:0xf bound_ctrl:1
	v_fmac_f32_e32 v2, v32, v26
	v_fmac_f32_e32 v3, v32, v27
	v_fma_f32 v0, -v4, v20, v0
	v_fma_f32 v1, -v4, v21, v1
	v_fma_f32 v2, -v4, v22, v2
	v_fma_f32 v3, -v4, v23, v3
	ds_read_b128 v[92:95], v6 offset:29184
	ds_read_b128 v[96:99], v6 offset:29440
	ds_read_b128 v[100:103], v6 offset:29696
	ds_read_b128 v[104:107], v6 offset:29952
	ds_read_b128 v[108:111], v6 offset:30208
	ds_read_b32 v112, v7 offset:29184
	s_waitcnt lgkmcnt(14)
	v_mul_f32_e32 v4, v0, v40
	v_mul_f32_e32 v5, v0, v52
	v_fmac_f32_e32 v4, v1, v41
	v_fmac_f32_e32 v5, v1, v53
	v_fmac_f32_e32 v4, v2, v42
	v_fmac_f32_e32 v5, v2, v54
	v_fmac_f32_e32 v4, v3, v43
	v_fmac_f32_e32 v5, v3, v55
	v_mul_f32_e32 v0, v0, v36
	v_add_f32_dpp v4, v4, v4 quad_perm:[1,0,3,2] row_mask:0xf bank_mask:0xf bound_ctrl:1
	v_mul_f32_e32 v1, v1, v37
	ds_write_b32 v8, v5 offset:1024
	v_add_f32_dpp v4, v4, v4 quad_perm:[2,3,0,1] row_mask:0xf bank_mask:0xf bound_ctrl:1
	v_mul_f32_e32 v2, v2, v38
	v_mul_f32_e32 v3, v3, v39
	v_add_f32_dpp v4, v4, v4 row_half_mirror row_mask:0xf bank_mask:0xf bound_ctrl:1
	v_fmac_f32_e32 v0, v56, v48
	v_fmac_f32_e32 v1, v56, v49
	v_add_f32_dpp v4, v4, v4 row_mirror row_mask:0xf bank_mask:0xf bound_ctrl:1
	v_fmac_f32_e32 v2, v56, v50
	v_fmac_f32_e32 v3, v56, v51
	v_fma_f32 v0, -v4, v44, v0
	v_fma_f32 v1, -v4, v45, v1
	v_fma_f32 v2, -v4, v46, v2
	v_fma_f32 v3, -v4, v47, v3
	ds_read_b128 v[12:15], v6 offset:30720
	ds_read_b128 v[16:19], v6 offset:30976
	ds_read_b128 v[20:23], v6 offset:31232
	ds_read_b128 v[24:27], v6 offset:31488
	ds_read_b128 v[28:31], v6 offset:31744
	ds_read_b32 v32, v7 offset:30720
	s_waitcnt lgkmcnt(14)
	v_mul_f32_e32 v4, v0, v72
	v_mul_f32_e32 v5, v0, v84
	v_fmac_f32_e32 v4, v1, v73
	v_fmac_f32_e32 v5, v1, v85
	v_fmac_f32_e32 v4, v2, v74
	v_fmac_f32_e32 v5, v2, v86
	v_fmac_f32_e32 v4, v3, v75
	v_fmac_f32_e32 v5, v3, v87
	v_mul_f32_e32 v0, v0, v68
	v_add_f32_dpp v4, v4, v4 quad_perm:[1,0,3,2] row_mask:0xf bank_mask:0xf bound_ctrl:1
	v_mul_f32_e32 v1, v1, v69
	ds_write_b32 v8, v5 offset:2048
	v_add_f32_dpp v4, v4, v4 quad_perm:[2,3,0,1] row_mask:0xf bank_mask:0xf bound_ctrl:1
	v_mul_f32_e32 v2, v2, v70
	v_mul_f32_e32 v3, v3, v71
	v_add_f32_dpp v4, v4, v4 row_half_mirror row_mask:0xf bank_mask:0xf bound_ctrl:1
	v_fmac_f32_e32 v0, v88, v80
	v_fmac_f32_e32 v1, v88, v81
	v_add_f32_dpp v4, v4, v4 row_mirror row_mask:0xf bank_mask:0xf bound_ctrl:1
	v_fmac_f32_e32 v2, v88, v82
	v_fmac_f32_e32 v3, v88, v83
	v_fma_f32 v0, -v4, v76, v0
	v_fma_f32 v1, -v4, v77, v1
	v_fma_f32 v2, -v4, v78, v2
	v_fma_f32 v3, -v4, v79, v3
	ds_read_b128 v[36:39], v6 offset:32256
	ds_read_b128 v[40:43], v6 offset:32512
	ds_read_b128 v[44:47], v6 offset:32768
	ds_read_b128 v[48:51], v6 offset:33024
	ds_read_b128 v[52:55], v6 offset:33280
	ds_read_b32 v56, v7 offset:32256
	s_waitcnt lgkmcnt(14)
	v_mul_f32_e32 v4, v0, v96
	v_mul_f32_e32 v5, v0, v108
	v_fmac_f32_e32 v4, v1, v97
	v_fmac_f32_e32 v5, v1, v109
	v_fmac_f32_e32 v4, v2, v98
	v_fmac_f32_e32 v5, v2, v110
	v_fmac_f32_e32 v4, v3, v99
	v_fmac_f32_e32 v5, v3, v111
	v_mul_f32_e32 v0, v0, v92
	v_add_f32_dpp v4, v4, v4 quad_perm:[1,0,3,2] row_mask:0xf bank_mask:0xf bound_ctrl:1
	v_mul_f32_e32 v1, v1, v93
	ds_write_b32 v8, v5 offset:3072
	v_add_f32_dpp v4, v4, v4 quad_perm:[2,3,0,1] row_mask:0xf bank_mask:0xf bound_ctrl:1
	v_mul_f32_e32 v2, v2, v94
	v_mul_f32_e32 v3, v3, v95
	v_add_f32_dpp v4, v4, v4 row_half_mirror row_mask:0xf bank_mask:0xf bound_ctrl:1
	v_fmac_f32_e32 v0, v112, v104
	v_fmac_f32_e32 v1, v112, v105
	v_add_f32_dpp v4, v4, v4 row_mirror row_mask:0xf bank_mask:0xf bound_ctrl:1
	v_fmac_f32_e32 v2, v112, v106
	v_fmac_f32_e32 v3, v112, v107
	v_fma_f32 v0, -v4, v100, v0
	v_fma_f32 v1, -v4, v101, v1
	v_fma_f32 v2, -v4, v102, v2
	v_fma_f32 v3, -v4, v103, v3
	ds_read_b128 v[68:71], v6 offset:33792
	ds_read_b128 v[72:75], v6 offset:34048
	ds_read_b128 v[76:79], v6 offset:34304
	ds_read_b128 v[80:83], v6 offset:34560
	ds_read_b128 v[84:87], v6 offset:34816
	ds_read_b32 v88, v7 offset:33792
	s_waitcnt lgkmcnt(14)
	v_mul_f32_e32 v4, v0, v16
	v_mul_f32_e32 v5, v0, v28
	v_fmac_f32_e32 v4, v1, v17
	v_fmac_f32_e32 v5, v1, v29
	v_fmac_f32_e32 v4, v2, v18
	v_fmac_f32_e32 v5, v2, v30
	v_fmac_f32_e32 v4, v3, v19
	v_fmac_f32_e32 v5, v3, v31
	v_mul_f32_e32 v0, v0, v12
	v_add_f32_dpp v4, v4, v4 quad_perm:[1,0,3,2] row_mask:0xf bank_mask:0xf bound_ctrl:1
	v_mul_f32_e32 v1, v1, v13
	ds_write_b32 v8, v5 offset:4096
	v_add_f32_dpp v4, v4, v4 quad_perm:[2,3,0,1] row_mask:0xf bank_mask:0xf bound_ctrl:1
	v_mul_f32_e32 v2, v2, v14
	v_mul_f32_e32 v3, v3, v15
	v_add_f32_dpp v4, v4, v4 row_half_mirror row_mask:0xf bank_mask:0xf bound_ctrl:1
	v_fmac_f32_e32 v0, v32, v24
	v_fmac_f32_e32 v1, v32, v25
	v_add_f32_dpp v4, v4, v4 row_mirror row_mask:0xf bank_mask:0xf bound_ctrl:1
	v_fmac_f32_e32 v2, v32, v26
	v_fmac_f32_e32 v3, v32, v27
	v_fma_f32 v0, -v4, v20, v0
	v_fma_f32 v1, -v4, v21, v1
	v_fma_f32 v2, -v4, v22, v2
	v_fma_f32 v3, -v4, v23, v3
	ds_read_b128 v[92:95], v6 offset:35328
	ds_read_b128 v[96:99], v6 offset:35584
	ds_read_b128 v[100:103], v6 offset:35840
	ds_read_b128 v[104:107], v6 offset:36096
	ds_read_b128 v[108:111], v6 offset:36352
	ds_read_b32 v112, v7 offset:35328
	s_waitcnt lgkmcnt(14)
	v_mul_f32_e32 v4, v0, v40
	v_mul_f32_e32 v5, v0, v52
	v_fmac_f32_e32 v4, v1, v41
	v_fmac_f32_e32 v5, v1, v53
	v_fmac_f32_e32 v4, v2, v42
	v_fmac_f32_e32 v5, v2, v54
	v_fmac_f32_e32 v4, v3, v43
	v_fmac_f32_e32 v5, v3, v55
	v_mul_f32_e32 v0, v0, v36
	v_add_f32_dpp v4, v4, v4 quad_perm:[1,0,3,2] row_mask:0xf bank_mask:0xf bound_ctrl:1
	v_mul_f32_e32 v1, v1, v37
	ds_write_b32 v8, v5 offset:5120
	v_add_f32_dpp v4, v4, v4 quad_perm:[2,3,0,1] row_mask:0xf bank_mask:0xf bound_ctrl:1
	v_mul_f32_e32 v2, v2, v38
	v_mul_f32_e32 v3, v3, v39
	v_add_f32_dpp v4, v4, v4 row_half_mirror row_mask:0xf bank_mask:0xf bound_ctrl:1
	v_fmac_f32_e32 v0, v56, v48
	v_fmac_f32_e32 v1, v56, v49
	v_add_f32_dpp v4, v4, v4 row_mirror row_mask:0xf bank_mask:0xf bound_ctrl:1
	v_fmac_f32_e32 v2, v56, v50
	v_fmac_f32_e32 v3, v56, v51
	v_fma_f32 v0, -v4, v44, v0
	v_fma_f32 v1, -v4, v45, v1
	v_fma_f32 v2, -v4, v46, v2
	v_fma_f32 v3, -v4, v47, v3
	ds_read_b128 v[12:15], v6 offset:36864
	ds_read_b128 v[16:19], v6 offset:37120
	ds_read_b128 v[20:23], v6 offset:37376
	ds_read_b128 v[24:27], v6 offset:37632
	ds_read_b128 v[28:31], v6 offset:37888
	ds_read_b32 v32, v7 offset:36864
	s_waitcnt lgkmcnt(14)
	v_mul_f32_e32 v4, v0, v72
	v_mul_f32_e32 v5, v0, v84
	v_fmac_f32_e32 v4, v1, v73
	v_fmac_f32_e32 v5, v1, v85
	v_fmac_f32_e32 v4, v2, v74
	v_fmac_f32_e32 v5, v2, v86
	v_fmac_f32_e32 v4, v3, v75
	v_fmac_f32_e32 v5, v3, v87
	v_mul_f32_e32 v0, v0, v68
	v_add_f32_dpp v4, v4, v4 quad_perm:[1,0,3,2] row_mask:0xf bank_mask:0xf bound_ctrl:1
	v_mul_f32_e32 v1, v1, v69
	ds_write_b32 v8, v5 offset:6144
	v_add_f32_dpp v4, v4, v4 quad_perm:[2,3,0,1] row_mask:0xf bank_mask:0xf bound_ctrl:1
	v_mul_f32_e32 v2, v2, v70
	v_mul_f32_e32 v3, v3, v71
	v_add_f32_dpp v4, v4, v4 row_half_mirror row_mask:0xf bank_mask:0xf bound_ctrl:1
	v_fmac_f32_e32 v0, v88, v80
	v_fmac_f32_e32 v1, v88, v81
	v_add_f32_dpp v4, v4, v4 row_mirror row_mask:0xf bank_mask:0xf bound_ctrl:1
	v_fmac_f32_e32 v2, v88, v82
	v_fmac_f32_e32 v3, v88, v83
	v_fma_f32 v0, -v4, v76, v0
	v_fma_f32 v1, -v4, v77, v1
	v_fma_f32 v2, -v4, v78, v2
	v_fma_f32 v3, -v4, v79, v3
	ds_read_b128 v[36:39], v6 offset:38400
	ds_read_b128 v[40:43], v6 offset:38656
	ds_read_b128 v[44:47], v6 offset:38912
	ds_read_b128 v[48:51], v6 offset:39168
	ds_read_b128 v[52:55], v6 offset:39424
	ds_read_b32 v56, v7 offset:38400
	s_waitcnt lgkmcnt(14)
	v_mul_f32_e32 v4, v0, v96
	v_mul_f32_e32 v5, v0, v108
	v_fmac_f32_e32 v4, v1, v97
	v_fmac_f32_e32 v5, v1, v109
	v_fmac_f32_e32 v4, v2, v98
	v_fmac_f32_e32 v5, v2, v110
	v_fmac_f32_e32 v4, v3, v99
	v_fmac_f32_e32 v5, v3, v111
	v_mul_f32_e32 v0, v0, v92
	v_add_f32_dpp v4, v4, v4 quad_perm:[1,0,3,2] row_mask:0xf bank_mask:0xf bound_ctrl:1
	v_mul_f32_e32 v1, v1, v93
	ds_write_b32 v8, v5 offset:7168
	v_add_f32_dpp v4, v4, v4 quad_perm:[2,3,0,1] row_mask:0xf bank_mask:0xf bound_ctrl:1
	v_mul_f32_e32 v2, v2, v94
	v_mul_f32_e32 v3, v3, v95
	v_add_f32_dpp v4, v4, v4 row_half_mirror row_mask:0xf bank_mask:0xf bound_ctrl:1
	v_fmac_f32_e32 v0, v112, v104
	v_fmac_f32_e32 v1, v112, v105
	v_add_f32_dpp v4, v4, v4 row_mirror row_mask:0xf bank_mask:0xf bound_ctrl:1
	v_fmac_f32_e32 v2, v112, v106
	v_fmac_f32_e32 v3, v112, v107
	v_fma_f32 v0, -v4, v100, v0
	v_fma_f32 v1, -v4, v101, v1
	v_fma_f32 v2, -v4, v102, v2
	v_fma_f32 v3, -v4, v103, v3
	ds_read_b128 v[68:71], v6 offset:39936
	ds_read_b128 v[72:75], v6 offset:40192
	ds_read_b128 v[76:79], v6 offset:40448
	ds_read_b128 v[80:83], v6 offset:40704
	ds_read_b128 v[84:87], v6 offset:40960
	ds_read_b32 v88, v7 offset:39936
	s_waitcnt lgkmcnt(6)
	s_barrier
	s_waitcnt lgkmcnt(14)
	v_mul_f32_e32 v4, v0, v16
	v_mul_f32_e32 v5, v0, v28
	v_fmac_f32_e32 v4, v1, v17
	v_fmac_f32_e32 v5, v1, v29
	v_fmac_f32_e32 v4, v2, v18
	v_fmac_f32_e32 v5, v2, v30
	v_fmac_f32_e32 v4, v3, v19
	v_fmac_f32_e32 v5, v3, v31
	v_mul_f32_e32 v0, v0, v12
	v_add_f32_dpp v4, v4, v4 quad_perm:[1,0,3,2] row_mask:0xf bank_mask:0xf bound_ctrl:1
	v_mul_f32_e32 v1, v1, v13
	ds_write_b32 v8, v5 offset:8192
	v_add_f32_dpp v4, v4, v4 quad_perm:[2,3,0,1] row_mask:0xf bank_mask:0xf bound_ctrl:1
	v_mul_f32_e32 v2, v2, v14
	v_mul_f32_e32 v3, v3, v15
	v_add_f32_dpp v4, v4, v4 row_half_mirror row_mask:0xf bank_mask:0xf bound_ctrl:1
	v_fmac_f32_e32 v0, v32, v24
	v_fmac_f32_e32 v1, v32, v25
	v_add_f32_dpp v4, v4, v4 row_mirror row_mask:0xf bank_mask:0xf bound_ctrl:1
	v_fmac_f32_e32 v2, v32, v26
	v_fmac_f32_e32 v3, v32, v27
	v_fma_f32 v0, -v4, v20, v0
	v_fma_f32 v1, -v4, v21, v1
	v_fma_f32 v2, -v4, v22, v2
	v_fma_f32 v3, -v4, v23, v3
	ds_read_b128 v[92:95], v6 offset:41472
	ds_read_b128 v[96:99], v6 offset:41728
	ds_read_b128 v[100:103], v6 offset:41984
	ds_read_b128 v[104:107], v6 offset:42240
	ds_read_b128 v[108:111], v6 offset:42496
	ds_read_b32 v112, v7 offset:41472
	s_waitcnt lgkmcnt(14)
	v_mul_f32_e32 v4, v0, v40
	v_mul_f32_e32 v5, v0, v52
	v_fmac_f32_e32 v4, v1, v41
	v_fmac_f32_e32 v5, v1, v53
	v_fmac_f32_e32 v4, v2, v42
	v_fmac_f32_e32 v5, v2, v54
	v_fmac_f32_e32 v4, v3, v43
	v_fmac_f32_e32 v5, v3, v55
	v_mul_f32_e32 v0, v0, v36
	v_add_f32_dpp v4, v4, v4 quad_perm:[1,0,3,2] row_mask:0xf bank_mask:0xf bound_ctrl:1
	v_mul_f32_e32 v1, v1, v37
	ds_write_b32 v8, v5 offset:9216
	v_add_f32_dpp v4, v4, v4 quad_perm:[2,3,0,1] row_mask:0xf bank_mask:0xf bound_ctrl:1
	v_mul_f32_e32 v2, v2, v38
	v_mul_f32_e32 v3, v3, v39
	v_add_f32_dpp v4, v4, v4 row_half_mirror row_mask:0xf bank_mask:0xf bound_ctrl:1
	v_fmac_f32_e32 v0, v56, v48
	v_fmac_f32_e32 v1, v56, v49
	v_add_f32_dpp v4, v4, v4 row_mirror row_mask:0xf bank_mask:0xf bound_ctrl:1
	v_fmac_f32_e32 v2, v56, v50
	v_fmac_f32_e32 v3, v56, v51
	v_fma_f32 v0, -v4, v44, v0
	v_fma_f32 v1, -v4, v45, v1
	v_fma_f32 v2, -v4, v46, v2
	v_fma_f32 v3, -v4, v47, v3
	ds_read_b128 v[12:15], v6 offset:43008
	ds_read_b128 v[16:19], v6 offset:43264
	ds_read_b128 v[20:23], v6 offset:43520
	ds_read_b128 v[24:27], v6 offset:43776
	ds_read_b128 v[28:31], v6 offset:44032
	ds_read_b32 v32, v7 offset:43008
	s_waitcnt lgkmcnt(14)
	v_mul_f32_e32 v4, v0, v72
	v_mul_f32_e32 v5, v0, v84
	v_fmac_f32_e32 v4, v1, v73
	v_fmac_f32_e32 v5, v1, v85
	v_fmac_f32_e32 v4, v2, v74
	v_fmac_f32_e32 v5, v2, v86
	v_fmac_f32_e32 v4, v3, v75
	v_fmac_f32_e32 v5, v3, v87
	v_mul_f32_e32 v0, v0, v68
	v_add_f32_dpp v4, v4, v4 quad_perm:[1,0,3,2] row_mask:0xf bank_mask:0xf bound_ctrl:1
	v_mul_f32_e32 v1, v1, v69
	ds_write_b32 v8, v5 offset:10240
	v_add_f32_dpp v4, v4, v4 quad_perm:[2,3,0,1] row_mask:0xf bank_mask:0xf bound_ctrl:1
	v_mul_f32_e32 v2, v2, v70
	v_mul_f32_e32 v3, v3, v71
	v_add_f32_dpp v4, v4, v4 row_half_mirror row_mask:0xf bank_mask:0xf bound_ctrl:1
	v_fmac_f32_e32 v0, v88, v80
	v_fmac_f32_e32 v1, v88, v81
	v_add_f32_dpp v4, v4, v4 row_mirror row_mask:0xf bank_mask:0xf bound_ctrl:1
	v_fmac_f32_e32 v2, v88, v82
	v_fmac_f32_e32 v3, v88, v83
	v_fma_f32 v0, -v4, v76, v0
	v_fma_f32 v1, -v4, v77, v1
	v_fma_f32 v2, -v4, v78, v2
	v_fma_f32 v3, -v4, v79, v3
	ds_read_b128 v[36:39], v6 offset:44544
	ds_read_b128 v[40:43], v6 offset:44800
	ds_read_b128 v[44:47], v6 offset:45056
	ds_read_b128 v[48:51], v6 offset:45312
	ds_read_b128 v[52:55], v6 offset:45568
	ds_read_b32 v56, v7 offset:44544
	s_waitcnt lgkmcnt(14)
	v_mul_f32_e32 v4, v0, v96
	v_mul_f32_e32 v5, v0, v108
	v_fmac_f32_e32 v4, v1, v97
	v_fmac_f32_e32 v5, v1, v109
	v_fmac_f32_e32 v4, v2, v98
	v_fmac_f32_e32 v5, v2, v110
	v_fmac_f32_e32 v4, v3, v99
	v_fmac_f32_e32 v5, v3, v111
	v_mul_f32_e32 v0, v0, v92
	v_add_f32_dpp v4, v4, v4 quad_perm:[1,0,3,2] row_mask:0xf bank_mask:0xf bound_ctrl:1
	v_mul_f32_e32 v1, v1, v93
	ds_write_b32 v8, v5 offset:11264
	v_add_f32_dpp v4, v4, v4 quad_perm:[2,3,0,1] row_mask:0xf bank_mask:0xf bound_ctrl:1
	v_mul_f32_e32 v2, v2, v94
	v_mul_f32_e32 v3, v3, v95
	v_add_f32_dpp v4, v4, v4 row_half_mirror row_mask:0xf bank_mask:0xf bound_ctrl:1
	v_fmac_f32_e32 v0, v112, v104
	v_fmac_f32_e32 v1, v112, v105
	v_add_f32_dpp v4, v4, v4 row_mirror row_mask:0xf bank_mask:0xf bound_ctrl:1
	v_fmac_f32_e32 v2, v112, v106
	v_fmac_f32_e32 v3, v112, v107
	v_fma_f32 v0, -v4, v100, v0
	v_fma_f32 v1, -v4, v101, v1
	v_fma_f32 v2, -v4, v102, v2
	v_fma_f32 v3, -v4, v103, v3
	ds_read_b128 v[68:71], v6 offset:46080
	ds_read_b128 v[72:75], v6 offset:46336
	ds_read_b128 v[76:79], v6 offset:46592
	ds_read_b128 v[80:83], v6 offset:46848
	ds_read_b128 v[84:87], v6 offset:47104
	ds_read_b32 v88, v7 offset:46080
	s_waitcnt lgkmcnt(14)
	v_mul_f32_e32 v4, v0, v16
	v_mul_f32_e32 v5, v0, v28
	v_fmac_f32_e32 v4, v1, v17
	v_fmac_f32_e32 v5, v1, v29
	v_fmac_f32_e32 v4, v2, v18
	v_fmac_f32_e32 v5, v2, v30
	v_fmac_f32_e32 v4, v3, v19
	v_fmac_f32_e32 v5, v3, v31
	v_mul_f32_e32 v0, v0, v12
	v_add_f32_dpp v4, v4, v4 quad_perm:[1,0,3,2] row_mask:0xf bank_mask:0xf bound_ctrl:1
	v_mul_f32_e32 v1, v1, v13
	ds_write_b32 v8, v5 offset:12288
	v_add_f32_dpp v4, v4, v4 quad_perm:[2,3,0,1] row_mask:0xf bank_mask:0xf bound_ctrl:1
	v_mul_f32_e32 v2, v2, v14
	v_mul_f32_e32 v3, v3, v15
	v_add_f32_dpp v4, v4, v4 row_half_mirror row_mask:0xf bank_mask:0xf bound_ctrl:1
	v_fmac_f32_e32 v0, v32, v24
	v_fmac_f32_e32 v1, v32, v25
	v_add_f32_dpp v4, v4, v4 row_mirror row_mask:0xf bank_mask:0xf bound_ctrl:1
	v_fmac_f32_e32 v2, v32, v26
	v_fmac_f32_e32 v3, v32, v27
	v_fma_f32 v0, -v4, v20, v0
	v_fma_f32 v1, -v4, v21, v1
	v_fma_f32 v2, -v4, v22, v2
	v_fma_f32 v3, -v4, v23, v3
	ds_read_b128 v[92:95], v6 offset:47616
	ds_read_b128 v[96:99], v6 offset:47872
	ds_read_b128 v[100:103], v6 offset:48128
	ds_read_b128 v[104:107], v6 offset:48384
	ds_read_b128 v[108:111], v6 offset:48640
	ds_read_b32 v112, v7 offset:47616
	s_waitcnt lgkmcnt(14)
	v_mul_f32_e32 v4, v0, v40
	v_mul_f32_e32 v5, v0, v52
	v_fmac_f32_e32 v4, v1, v41
	v_fmac_f32_e32 v5, v1, v53
	v_fmac_f32_e32 v4, v2, v42
	v_fmac_f32_e32 v5, v2, v54
	v_fmac_f32_e32 v4, v3, v43
	v_fmac_f32_e32 v5, v3, v55
	v_mul_f32_e32 v0, v0, v36
	v_add_f32_dpp v4, v4, v4 quad_perm:[1,0,3,2] row_mask:0xf bank_mask:0xf bound_ctrl:1
	v_mul_f32_e32 v1, v1, v37
	ds_write_b32 v8, v5 offset:13312
	v_add_f32_dpp v4, v4, v4 quad_perm:[2,3,0,1] row_mask:0xf bank_mask:0xf bound_ctrl:1
	v_mul_f32_e32 v2, v2, v38
	v_mul_f32_e32 v3, v3, v39
	v_add_f32_dpp v4, v4, v4 row_half_mirror row_mask:0xf bank_mask:0xf bound_ctrl:1
	v_fmac_f32_e32 v0, v56, v48
	v_fmac_f32_e32 v1, v56, v49
	v_add_f32_dpp v4, v4, v4 row_mirror row_mask:0xf bank_mask:0xf bound_ctrl:1
	v_fmac_f32_e32 v2, v56, v50
	v_fmac_f32_e32 v3, v56, v51
	v_fma_f32 v0, -v4, v44, v0
	v_fma_f32 v1, -v4, v45, v1
	v_fma_f32 v2, -v4, v46, v2
	v_fma_f32 v3, -v4, v47, v3
	ds_read_b128 v[12:15], v6 offset:0
	ds_read_b128 v[16:19], v6 offset:256
	ds_read_b128 v[20:23], v6 offset:512
	ds_read_b128 v[24:27], v6 offset:768
	ds_read_b128 v[28:31], v6 offset:1024
	ds_read_b32 v32, v7 offset:0
	s_waitcnt lgkmcnt(14)
	v_mul_f32_e32 v4, v0, v72
	v_mul_f32_e32 v5, v0, v84
	v_fmac_f32_e32 v4, v1, v73
	v_fmac_f32_e32 v5, v1, v85
	v_fmac_f32_e32 v4, v2, v74
	v_fmac_f32_e32 v5, v2, v86
	v_fmac_f32_e32 v4, v3, v75
	v_fmac_f32_e32 v5, v3, v87
	v_mul_f32_e32 v0, v0, v68
	v_add_f32_dpp v4, v4, v4 quad_perm:[1,0,3,2] row_mask:0xf bank_mask:0xf bound_ctrl:1
	v_mul_f32_e32 v1, v1, v69
	ds_write_b32 v8, v5 offset:14336
	v_add_f32_dpp v4, v4, v4 quad_perm:[2,3,0,1] row_mask:0xf bank_mask:0xf bound_ctrl:1
	v_mul_f32_e32 v2, v2, v70
	v_mul_f32_e32 v3, v3, v71
	v_add_f32_dpp v4, v4, v4 row_half_mirror row_mask:0xf bank_mask:0xf bound_ctrl:1
	v_fmac_f32_e32 v0, v88, v80
	v_fmac_f32_e32 v1, v88, v81
	v_add_f32_dpp v4, v4, v4 row_mirror row_mask:0xf bank_mask:0xf bound_ctrl:1
	v_fmac_f32_e32 v2, v88, v82
	v_fmac_f32_e32 v3, v88, v83
	v_fma_f32 v0, -v4, v76, v0
	v_fma_f32 v1, -v4, v77, v1
	v_fma_f32 v2, -v4, v78, v2
	v_fma_f32 v3, -v4, v79, v3
	ds_read_b128 v[36:39], v6 offset:1536
	ds_read_b128 v[40:43], v6 offset:1792
	ds_read_b128 v[44:47], v6 offset:2048
	ds_read_b128 v[48:51], v6 offset:2304
	ds_read_b128 v[52:55], v6 offset:2560
	ds_read_b32 v56, v7 offset:1536
	s_waitcnt lgkmcnt(14)
	v_mul_f32_e32 v4, v0, v96
	v_mul_f32_e32 v5, v0, v108
	v_fmac_f32_e32 v4, v1, v97
	v_fmac_f32_e32 v5, v1, v109
	v_fmac_f32_e32 v4, v2, v98
	v_fmac_f32_e32 v5, v2, v110
	v_fmac_f32_e32 v4, v3, v99
	v_fmac_f32_e32 v5, v3, v111
	v_mul_f32_e32 v0, v0, v92
	v_add_f32_dpp v4, v4, v4 quad_perm:[1,0,3,2] row_mask:0xf bank_mask:0xf bound_ctrl:1
	v_mul_f32_e32 v1, v1, v93
	ds_write_b32 v8, v5 offset:15360
	v_add_f32_dpp v4, v4, v4 quad_perm:[2,3,0,1] row_mask:0xf bank_mask:0xf bound_ctrl:1
	v_mul_f32_e32 v2, v2, v94
	v_mul_f32_e32 v3, v3, v95
	v_add_f32_dpp v4, v4, v4 row_half_mirror row_mask:0xf bank_mask:0xf bound_ctrl:1
	v_fmac_f32_e32 v0, v112, v104
	v_fmac_f32_e32 v1, v112, v105
	v_add_f32_dpp v4, v4, v4 row_mirror row_mask:0xf bank_mask:0xf bound_ctrl:1
	v_fmac_f32_e32 v2, v112, v106
	v_fmac_f32_e32 v3, v112, v107
	v_fma_f32 v0, -v4, v100, v0
	v_fma_f32 v1, -v4, v101, v1
	v_fma_f32 v2, -v4, v102, v2
	v_fma_f32 v3, -v4, v103, v3
	ds_read_b128 v[68:71], v6 offset:3072
	ds_read_b128 v[72:75], v6 offset:3328
	ds_read_b128 v[76:79], v6 offset:3584
	ds_read_b128 v[80:83], v6 offset:3840
	ds_read_b128 v[84:87], v6 offset:4096
	ds_read_b32 v88, v7 offset:3072
	s_waitcnt lgkmcnt(6)
	s_barrier
	s_sub_u32 s34, s34, 1
	s_cmp_lg_u32 s34, 0
	s_cbranch_scc1 .Lb2_scan_loop
	s_setprio 0
	s_waitcnt lgkmcnt(0)
	global_store_dwordx4 v9, v[0:3], s[40:41]
	s_branch .Lb2_u_next
.Lb2_loader:
	v_add_u32_e32 v61, 0xffffff00, v133
	v_lshrrev_b32_e32 v62, 5, v61
	v_mul_u32_u24_e32 v48, 0x600, v62
	v_and_b32_e32 v63, 31, v61
	v_lshl_add_u32 v48, v63, 4, v48
	v_add_u32_e32 v49, 0x3000, v48
	v_lshlrev_b32_e32 v51, 5, v61
	v_add_u32_e32 v51, 0xc000, v51
	v_lshlrev_b32_e32 v60, 11, v62
	v_bfe_u32 v63, v61, 1, 4
	v_lshl_add_u32 v60, v63, 2, v60
	s_lshr_b32 s21, s20, 3
	s_lshl_b32 s21, s21, 22
	s_and_b32 s23, s20, 7
	s_lshl_b32 s23, s23, 8
	s_add_i32 s21, s21, s23
	s_lshl_b32 s23, s33, 6
	s_add_i32 s21, s21, s23
	s_add_u32 s21, s21, 0x19314000
	s_add_u32 s36, s94, s21
	s_addc_u32 s37, s95, 0
	s_mov_b32 s38, 0x55555555
	s_mov_b32 s39, 0x55555555
	s_movk_i32 s34, 0x40
	s_mov_b32 s35, 0
	global_load_dwordx4 v[0:3], v48, s[28:29]
	global_load_dwordx4 v[4:7], v48, s[28:29] offset:512
	global_load_dwordx4 v[8:11], v48, s[28:29] offset:1024
	global_load_dwordx4 v[12:15], v49, s[28:29]
	global_load_dwordx4 v[16:19], v49, s[28:29] offset:512
	global_load_dwordx4 v[20:23], v49, s[28:29] offset:1024
	s_add_u32 s28, s28, 0x6000
	s_addc_u32 s29, s29, 0
	global_load_dwordx4 v[24:27], v48, s[28:29]
	global_load_dwordx4 v[28:31], v48, s[28:29] offset:512
	global_load_dwordx4 v[32:35], v48, s[28:29] offset:1024
	global_load_dwordx4 v[36:39], v49, s[28:29]
	global_load_dwordx4 v[40:43], v49, s[28:29] offset:512
	global_load_dwordx4 v[44:47], v49, s[28:29] offset:1024
	s_add_u32 s28, s28, 0x6000
	s_addc_u32 s29, s29, 0
	s_waitcnt vmcnt(6)
	ds_write_b128 v48, v[0:3] offset:0
	ds_write_b128 v48, v[4:7] offset:512
	ds_write_b128 v48, v[8:11] offset:1024
	ds_write_b128 v48, v[12:15] offset:12288
	ds_write_b128 v48, v[16:19] offset:12800
	ds_write_b128 v48, v[20:23] offset:13312
	global_load_dwordx4 v[0:3], v48, s[28:29]
	global_load_dwordx4 v[4:7], v48, s[28:29] offset:512
	global_load_dwordx4 v[8:11], v48, s[28:29] offset:1024
	global_load_dwordx4 v[12:15], v49, s[28:29]
	global_load_dwordx4 v[16:19], v49, s[28:29] offset:512
	global_load_dwordx4 v[20:23], v49, s[28:29] offset:1024
	s_add_u32 s28, s28, 0x6000
	s_addc_u32 s29, s29, 0
	s_waitcnt lgkmcnt(0)
	s_barrier
.Lb2_load_loop:
	s_cmp_eq_u32 s35, 0
	s_cbranch_scc1 .Lb2_ld_first
	ds_read_b128 v[52:55], v51 offset:8192
	ds_read_b128 v[56:59], v51 offset:8208
	s_waitcnt lgkmcnt(1)
	v_add_f32_e32 v52, v52, v53
	v_add_f32_e32 v54, v54, v55
	s_waitcnt lgkmcnt(0)
	v_add_f32_e32 v56, v56, v57
	v_add_f32_e32 v58, v58, v59
	v_add_f32_e32 v52, v52, v54
	v_add_f32_e32 v56, v56, v58
	v_add_f32_e32 v52, v52, v56
	s_nop 1
	v_add_f32_dpp v52, v52, v52 quad_perm:[1,0,3,2] row_mask:0xf bank_mask:0xf bound_ctrl:1
	s_mov_b64 exec, s[38:39]
	global_store_dword v60, v52, s[36:37]
	s_mov_b64 exec, -1
	s_add_u32 s36, s36, 0x4000
	s_addc_u32 s37, s37, 0
.Lb2_ld_first:
	s_mov_b32 s35, 1
	s_waitcnt vmcnt(6)
	ds_write_b128 v48, v[24:27] offset:24576
	ds_write_b128 v48, v[28:31] offset:25088
	ds_write_b128 v48, v[32:35] offset:25600
	ds_write_b128 v48, v[36:39] offset:36864
	ds_write_b128 v48, v[40:43] offset:37376
	ds_write_b128 v48, v[44:47] offset:37888
	global_load_dwordx4 v[24:27], v48, s[28:29]
	global_load_dwordx4 v[28:31], v48, s[28:29] offset:512
	global_load_dwordx4 v[32:35], v48, s[28:29] offset:1024
	global_load_dwordx4 v[36:39], v49, s[28:29]
	global_load_dwordx4 v[40:43], v49, s[28:29] offset:512
	global_load_dwordx4 v[44:47], v49, s[28:29] offset:1024
	s_add_u32 s28, s28, 0x6000
	s_addc_u32 s29, s29, 0
	s_waitcnt lgkmcnt(0)
	s_barrier
	ds_read_b128 v[52:55], v51 offset:0
	ds_read_b128 v[56:59], v51 offset:16
	s_waitcnt lgkmcnt(1)
	v_add_f32_e32 v52, v52, v53
	v_add_f32_e32 v54, v54, v55
	s_waitcnt lgkmcnt(0)
	v_add_f32_e32 v56, v56, v57
	v_add_f32_e32 v58, v58, v59
	v_add_f32_e32 v52, v52, v54
	v_add_f32_e32 v56, v56, v58
	v_add_f32_e32 v52, v52, v56
	s_nop 1
	v_add_f32_dpp v52, v52, v52 quad_perm:[1,0,3,2] row_mask:0xf bank_mask:0xf bound_ctrl:1
	s_mov_b64 exec, s[38:39]
	global_store_dword v60, v52, s[36:37]
	s_mov_b64 exec, -1
	s_add_u32 s36, s36, 0x4000
	s_addc_u32 s37, s37, 0
	s_waitcnt lgkmcnt(0)
	s_barrier
	ds_read_b128 v[52:55], v51 offset:8192
	ds_read_b128 v[56:59], v51 offset:8208
	s_waitcnt lgkmcnt(1)
	v_add_f32_e32 v52, v52, v53
	v_add_f32_e32 v54, v54, v55
	s_waitcnt lgkmcnt(0)
	v_add_f32_e32 v56, v56, v57
	v_add_f32_e32 v58, v58, v59
	v_add_f32_e32 v52, v52, v54
	v_add_f32_e32 v56, v56, v58
	v_add_f32_e32 v52, v52, v56
	s_nop 1
	v_add_f32_dpp v52, v52, v52 quad_perm:[1,0,3,2] row_mask:0xf bank_mask:0xf bound_ctrl:1
	s_mov_b64 exec, s[38:39]
	global_store_dword v60, v52, s[36:37]
	s_mov_b64 exec, -1
	s_add_u32 s36, s36, 0x4000
	s_addc_u32 s37, s37, 0
	s_waitcnt vmcnt(6)
	ds_write_b128 v48, v[0:3] offset:0
	ds_write_b128 v48, v[4:7] offset:512
	ds_write_b128 v48, v[8:11] offset:1024
	ds_write_b128 v48, v[12:15] offset:12288
	ds_write_b128 v48, v[16:19] offset:12800
	ds_write_b128 v48, v[20:23] offset:13312
	global_load_dwordx4 v[0:3], v48, s[28:29]
	global_load_dwordx4 v[4:7], v48, s[28:29] offset:512
	global_load_dwordx4 v[8:11], v48, s[28:29] offset:1024
	global_load_dwordx4 v[12:15], v49, s[28:29]
	global_load_dwordx4 v[16:19], v49, s[28:29] offset:512
	global_load_dwordx4 v[20:23], v49, s[28:29] offset:1024
	s_add_u32 s28, s28, 0x6000
	s_addc_u32 s29, s29, 0
	s_waitcnt lgkmcnt(0)
	s_barrier
	ds_read_b128 v[52:55], v51 offset:0
	ds_read_b128 v[56:59], v51 offset:16
	s_waitcnt lgkmcnt(1)
	v_add_f32_e32 v52, v52, v53
	v_add_f32_e32 v54, v54, v55
	s_waitcnt lgkmcnt(0)
	v_add_f32_e32 v56, v56, v57
	v_add_f32_e32 v58, v58, v59
	v_add_f32_e32 v52, v52, v54
	v_add_f32_e32 v56, v56, v58
	v_add_f32_e32 v52, v52, v56
	s_nop 1
	v_add_f32_dpp v52, v52, v52 quad_perm:[1,0,3,2] row_mask:0xf bank_mask:0xf bound_ctrl:1
	s_mov_b64 exec, s[38:39]
	global_store_dword v60, v52, s[36:37]
	s_mov_b64 exec, -1
	s_add_u32 s36, s36, 0x4000
	s_addc_u32 s37, s37, 0
	s_waitcnt lgkmcnt(0)
	s_barrier
	s_sub_u32 s34, s34, 1
	s_cmp_lg_u32 s34, 0
	s_cbranch_scc1 .Lb2_load_loop
	ds_read_b128 v[52:55], v51 offset:8192
	ds_read_b128 v[56:59], v51 offset:8208
	s_waitcnt lgkmcnt(1)
	v_add_f32_e32 v52, v52, v53
	v_add_f32_e32 v54, v54, v55
	s_waitcnt lgkmcnt(0)
	v_add_f32_e32 v56, v56, v57
	v_add_f32_e32 v58, v58, v59
	v_add_f32_e32 v52, v52, v54
	v_add_f32_e32 v56, v56, v58
	v_add_f32_e32 v52, v52, v56
	s_nop 1
	v_add_f32_dpp v52, v52, v52 quad_perm:[1,0,3,2] row_mask:0xf bank_mask:0xf bound_ctrl:1
	s_mov_b64 exec, s[38:39]
	global_store_dword v60, v52, s[36:37]
	s_mov_b64 exec, -1
	s_add_u32 s36, s36, 0x4000
	s_addc_u32 s37, s37, 0
.Lb2_u_next:
	v_readlane_b32 s20, v216, 3
	s_add_i32 s22, s22, s20
	s_cmpk_gt_i32 s22, 0xff
	s_cbranch_scc1 .LBB0_316
	s_branch .Lb2_u_loop
